# attention P.V: counted lgkmcnt wait ahead of every MFMA (each waits only for its own two transposed V reads) instead of lgkmcnt(0) per group of four
# speedup vs baseline: 1.0012x; 1.0011x over previous
.LBB0_467:
	v_add_f32_e32 v97, v97, v98
	v_fmac_f32_e32 v97, v204, v96
	v_cvt_pk_bf16_f32 v64, v64, v65
	v_cvt_pk_bf16_f32 v65, v66, v67
	v_cvt_pk_bf16_f32 v66, v81, v83
	v_cvt_pk_bf16_f32 v67, v85, v88
	v_cvt_pk_bf16_f32 v88, v86, v89
	v_cvt_pk_bf16_f32 v89, v90, v91
	v_cvt_pk_bf16_f32 v90, v92, v93
	v_cvt_pk_bf16_f32 v91, v94, v95
	v_cvt_pk_bf16_f32 v68, v68, v69
	v_cvt_pk_bf16_f32 v69, v70, v71
	v_cvt_pk_bf16_f32 v70, v72, v73
	v_cvt_pk_bf16_f32 v71, v74, v76
	v_cvt_pk_bf16_f32 v72, v75, v77
	v_cvt_pk_bf16_f32 v73, v78, v79
	v_cvt_pk_bf16_f32 v74, v80, v82
	v_cvt_pk_bf16_f32 v75, v84, v87
	v_add_u32_e32 v96, s82, v201
	ds_read_b64_tr_b16 v[76:77], v96 offset:0
	ds_read_b64_tr_b16 v[78:79], v96 offset:0x800
	ds_read_b64_tr_b16 v[80:81], v96 offset:0x1000
	ds_read_b64_tr_b16 v[82:83], v96 offset:0x1800
	ds_read_b64_tr_b16 v[84:85], v96 offset:0x2000
	ds_read_b64_tr_b16 v[86:87], v96 offset:0x2800
	ds_read_b64_tr_b16 v[92:93], v96 offset:0x3000
	ds_read_b64_tr_b16 v[94:95], v96 offset:0x3800
	s_waitcnt lgkmcnt(15)
	v_permlane32_swap_b32_e32 v64, v66
	v_permlane32_swap_b32_e32 v65, v67
	v_permlane32_swap_b32_e32 v88, v90
	v_permlane32_swap_b32_e32 v89, v91
	v_permlane32_swap_b32_e32 v68, v70
	v_permlane32_swap_b32_e32 v69, v71
	v_permlane32_swap_b32_e32 v72, v74
	v_permlane32_swap_b32_e32 v73, v75
	s_waitcnt lgkmcnt(6)
	v_mfma_f32_32x32x16_bf16 v[0:15], v[64:67], v[76:79], v[0:15]
	ds_read_b64_tr_b16 v[76:77], v96 offset:0x200
	ds_read_b64_tr_b16 v[78:79], v96 offset:0xa00
	s_waitcnt lgkmcnt(6)
	v_mfma_f32_32x32x16_bf16 v[0:15], v[88:91], v[80:83], v[0:15]
	ds_read_b64_tr_b16 v[80:81], v96 offset:0x1200
	ds_read_b64_tr_b16 v[82:83], v96 offset:0x1a00
	s_waitcnt lgkmcnt(6)
	v_mfma_f32_32x32x16_bf16 v[0:15], v[68:71], v[84:87], v[0:15]
	ds_read_b64_tr_b16 v[84:85], v96 offset:0x2200
	ds_read_b64_tr_b16 v[86:87], v96 offset:0x2a00
	s_waitcnt lgkmcnt(6)
	v_mfma_f32_32x32x16_bf16 v[0:15], v[72:75], v[92:95], v[0:15]
	ds_read_b64_tr_b16 v[92:93], v96 offset:0x3200
	ds_read_b64_tr_b16 v[94:95], v96 offset:0x3a00
	s_waitcnt lgkmcnt(15)
	s_waitcnt lgkmcnt(6)
	v_mfma_f32_32x32x16_bf16 v[48:63], v[64:67], v[76:79], v[48:63]
	ds_read_b64_tr_b16 v[76:77], v96 offset:0x400
	ds_read_b64_tr_b16 v[78:79], v96 offset:0xc00
	s_waitcnt lgkmcnt(6)
	v_mfma_f32_32x32x16_bf16 v[48:63], v[88:91], v[80:83], v[48:63]
	ds_read_b64_tr_b16 v[80:81], v96 offset:0x1400
	ds_read_b64_tr_b16 v[82:83], v96 offset:0x1c00
	s_waitcnt lgkmcnt(6)
	v_mfma_f32_32x32x16_bf16 v[48:63], v[68:71], v[84:87], v[48:63]
	ds_read_b64_tr_b16 v[84:85], v96 offset:0x2400
	ds_read_b64_tr_b16 v[86:87], v96 offset:0x2c00
	s_waitcnt lgkmcnt(6)
	v_mfma_f32_32x32x16_bf16 v[48:63], v[72:75], v[92:95], v[48:63]
	ds_read_b64_tr_b16 v[92:93], v96 offset:0x3400
	ds_read_b64_tr_b16 v[94:95], v96 offset:0x3c00
	s_waitcnt lgkmcnt(15)
	s_waitcnt lgkmcnt(6)
	v_mfma_f32_32x32x16_bf16 v[32:47], v[64:67], v[76:79], v[32:47]
	ds_read_b64_tr_b16 v[76:77], v96 offset:0x600
	ds_read_b64_tr_b16 v[78:79], v96 offset:0xe00
	s_waitcnt lgkmcnt(6)
	v_mfma_f32_32x32x16_bf16 v[32:47], v[88:91], v[80:83], v[32:47]
	ds_read_b64_tr_b16 v[80:81], v96 offset:0x1600
	ds_read_b64_tr_b16 v[82:83], v96 offset:0x1e00
	s_waitcnt lgkmcnt(6)
	v_mfma_f32_32x32x16_bf16 v[32:47], v[68:71], v[84:87], v[32:47]
	ds_read_b64_tr_b16 v[84:85], v96 offset:0x2600
	ds_read_b64_tr_b16 v[86:87], v96 offset:0x2e00
	s_waitcnt lgkmcnt(6)
	v_mfma_f32_32x32x16_bf16 v[32:47], v[72:75], v[92:95], v[32:47]
	ds_read_b64_tr_b16 v[92:93], v96 offset:0x3600
	ds_read_b64_tr_b16 v[94:95], v96 offset:0x3e00
	s_waitcnt lgkmcnt(15)
	s_waitcnt lgkmcnt(6)
	v_mfma_f32_32x32x16_bf16 v[16:31], v[64:67], v[76:79], v[16:31]
	v_mov_b32_e32 v204, v97
	s_waitcnt lgkmcnt(4)
	v_mfma_f32_32x32x16_bf16 v[16:31], v[88:91], v[80:83], v[16:31]
	s_waitcnt lgkmcnt(2)
	v_mfma_f32_32x32x16_bf16 v[16:31], v[68:71], v[84:87], v[16:31]
	s_waitcnt lgkmcnt(0)
	v_mfma_f32_32x32x16_bf16 v[16:31], v[72:75], v[92:95], v[16:31]

.LBB0_481:
	v_add_f32_e32 v97, v97, v98
	v_fmac_f32_e32 v97, v186, v96
	v_cvt_pk_bf16_f32 v64, v64, v65
	v_cvt_pk_bf16_f32 v65, v66, v67
	v_cvt_pk_bf16_f32 v66, v81, v83
	v_cvt_pk_bf16_f32 v67, v85, v88
	v_cvt_pk_bf16_f32 v88, v86, v89
	v_cvt_pk_bf16_f32 v89, v90, v91
	v_cvt_pk_bf16_f32 v90, v92, v93
	v_cvt_pk_bf16_f32 v91, v94, v95
	v_cvt_pk_bf16_f32 v68, v68, v69
	v_cvt_pk_bf16_f32 v69, v70, v71
	v_cvt_pk_bf16_f32 v70, v72, v73
	v_cvt_pk_bf16_f32 v71, v74, v76
	v_cvt_pk_bf16_f32 v72, v75, v77
	v_cvt_pk_bf16_f32 v73, v78, v79
	v_cvt_pk_bf16_f32 v74, v80, v82
	v_cvt_pk_bf16_f32 v75, v84, v87
	v_add_u32_e32 v96, s54, v185
	ds_read_b64_tr_b16 v[76:77], v96 offset:0
	ds_read_b64_tr_b16 v[78:79], v96 offset:0x800
	ds_read_b64_tr_b16 v[80:81], v96 offset:0x1000
	ds_read_b64_tr_b16 v[82:83], v96 offset:0x1800
	ds_read_b64_tr_b16 v[84:85], v96 offset:0x2000
	ds_read_b64_tr_b16 v[86:87], v96 offset:0x2800
	ds_read_b64_tr_b16 v[92:93], v96 offset:0x3000
	ds_read_b64_tr_b16 v[94:95], v96 offset:0x3800
	s_waitcnt lgkmcnt(15)
	v_permlane32_swap_b32_e32 v64, v66
	v_permlane32_swap_b32_e32 v65, v67
	v_permlane32_swap_b32_e32 v88, v90
	v_permlane32_swap_b32_e32 v89, v91
	v_permlane32_swap_b32_e32 v68, v70
	v_permlane32_swap_b32_e32 v69, v71
	v_permlane32_swap_b32_e32 v72, v74
	v_permlane32_swap_b32_e32 v73, v75
	s_waitcnt lgkmcnt(6)
	v_mfma_f32_32x32x16_bf16 v[0:15], v[64:67], v[76:79], v[0:15]
	ds_read_b64_tr_b16 v[76:77], v96 offset:0x200
	ds_read_b64_tr_b16 v[78:79], v96 offset:0xa00
	s_waitcnt lgkmcnt(6)
	v_mfma_f32_32x32x16_bf16 v[0:15], v[88:91], v[80:83], v[0:15]
	ds_read_b64_tr_b16 v[80:81], v96 offset:0x1200
	ds_read_b64_tr_b16 v[82:83], v96 offset:0x1a00
	s_waitcnt lgkmcnt(6)
	v_mfma_f32_32x32x16_bf16 v[0:15], v[68:71], v[84:87], v[0:15]
	ds_read_b64_tr_b16 v[84:85], v96 offset:0x2200
	ds_read_b64_tr_b16 v[86:87], v96 offset:0x2a00
	s_waitcnt lgkmcnt(6)
	v_mfma_f32_32x32x16_bf16 v[0:15], v[72:75], v[92:95], v[0:15]
	ds_read_b64_tr_b16 v[92:93], v96 offset:0x3200
	ds_read_b64_tr_b16 v[94:95], v96 offset:0x3a00
	s_waitcnt lgkmcnt(15)
	s_waitcnt lgkmcnt(6)
	v_mfma_f32_32x32x16_bf16 v[48:63], v[64:67], v[76:79], v[48:63]
	ds_read_b64_tr_b16 v[76:77], v96 offset:0x400
	ds_read_b64_tr_b16 v[78:79], v96 offset:0xc00
	s_waitcnt lgkmcnt(6)
	v_mfma_f32_32x32x16_bf16 v[48:63], v[88:91], v[80:83], v[48:63]
	ds_read_b64_tr_b16 v[80:81], v96 offset:0x1400
	ds_read_b64_tr_b16 v[82:83], v96 offset:0x1c00
	s_waitcnt lgkmcnt(6)
	v_mfma_f32_32x32x16_bf16 v[48:63], v[68:71], v[84:87], v[48:63]
	ds_read_b64_tr_b16 v[84:85], v96 offset:0x2400
	ds_read_b64_tr_b16 v[86:87], v96 offset:0x2c00
	s_waitcnt lgkmcnt(6)
	v_mfma_f32_32x32x16_bf16 v[48:63], v[72:75], v[92:95], v[48:63]
	ds_read_b64_tr_b16 v[92:93], v96 offset:0x3400
	ds_read_b64_tr_b16 v[94:95], v96 offset:0x3c00
	s_waitcnt lgkmcnt(15)
	s_waitcnt lgkmcnt(6)
	v_mfma_f32_32x32x16_bf16 v[32:47], v[64:67], v[76:79], v[32:47]
	ds_read_b64_tr_b16 v[76:77], v96 offset:0x600
	ds_read_b64_tr_b16 v[78:79], v96 offset:0xe00
	s_waitcnt lgkmcnt(6)
	v_mfma_f32_32x32x16_bf16 v[32:47], v[88:91], v[80:83], v[32:47]
	ds_read_b64_tr_b16 v[80:81], v96 offset:0x1600
	ds_read_b64_tr_b16 v[82:83], v96 offset:0x1e00
	s_waitcnt lgkmcnt(6)
	v_mfma_f32_32x32x16_bf16 v[32:47], v[68:71], v[84:87], v[32:47]
	ds_read_b64_tr_b16 v[84:85], v96 offset:0x2600
	ds_read_b64_tr_b16 v[86:87], v96 offset:0x2e00
	s_waitcnt lgkmcnt(6)
	v_mfma_f32_32x32x16_bf16 v[32:47], v[72:75], v[92:95], v[32:47]
	ds_read_b64_tr_b16 v[92:93], v96 offset:0x3600
	ds_read_b64_tr_b16 v[94:95], v96 offset:0x3e00
	s_waitcnt lgkmcnt(15)
	s_waitcnt lgkmcnt(6)
	v_mfma_f32_32x32x16_bf16 v[16:31], v[64:67], v[76:79], v[16:31]
	v_mov_b32_e32 v186, v97
	s_waitcnt lgkmcnt(4)
	v_mfma_f32_32x32x16_bf16 v[16:31], v[88:91], v[80:83], v[16:31]
	s_waitcnt lgkmcnt(2)
	v_mfma_f32_32x32x16_bf16 v[16:31], v[68:71], v[84:87], v[16:31]
	s_waitcnt lgkmcnt(0)
	v_mfma_f32_32x32x16_bf16 v[16:31], v[72:75], v[92:95], v[16:31]

.LBB0_500:
	v_add_f32_e32 v100, v97, v98
	v_fmac_f32_e32 v100, v186, v96
	v_cvt_pk_bf16_f32 v96, v72, v75
	v_cvt_pk_bf16_f32 v97, v77, v79
	v_cvt_pk_bf16_f32 v98, v81, v83
	v_cvt_pk_bf16_f32 v99, v85, v88
	v_cvt_pk_bf16_f32 v88, v86, v89
	v_cvt_pk_bf16_f32 v89, v90, v91
	v_cvt_pk_bf16_f32 v90, v92, v93
	v_cvt_pk_bf16_f32 v91, v94, v95
	v_cvt_pk_bf16_f32 v64, v64, v65
	v_cvt_pk_bf16_f32 v65, v66, v67
	v_cvt_pk_bf16_f32 v66, v68, v69
	v_cvt_pk_bf16_f32 v67, v70, v73
	v_cvt_pk_bf16_f32 v68, v71, v74
	v_cvt_pk_bf16_f32 v69, v76, v78
	v_cvt_pk_bf16_f32 v70, v80, v82
	v_cvt_pk_bf16_f32 v71, v84, v87
	ds_read_b64_tr_b16 v[72:73], v185 offset:0
	ds_read_b64_tr_b16 v[74:75], v185 offset:0x800
	ds_read_b64_tr_b16 v[76:77], v185 offset:0x1000
	ds_read_b64_tr_b16 v[78:79], v185 offset:0x1800
	ds_read_b64_tr_b16 v[80:81], v185 offset:0x2000
	ds_read_b64_tr_b16 v[82:83], v185 offset:0x2800
	ds_read_b64_tr_b16 v[84:85], v185 offset:0x3000
	ds_read_b64_tr_b16 v[86:87], v185 offset:0x3800
	s_waitcnt lgkmcnt(0)
	s_nop 0
	v_permlane32_swap_b32_e32 v96, v98
	v_permlane32_swap_b32_e32 v97, v99
	v_permlane32_swap_b32_e32 v88, v90
	v_permlane32_swap_b32_e32 v89, v91
	v_permlane32_swap_b32_e32 v64, v66
	v_permlane32_swap_b32_e32 v65, v67
	v_permlane32_swap_b32_e32 v68, v70
	v_permlane32_swap_b32_e32 v69, v71
	s_waitcnt lgkmcnt(6)
	v_mfma_f32_32x32x16_bf16 v[0:15], v[96:99], v[72:75], v[0:15]
	ds_read_b64_tr_b16 v[72:73], v185 offset:0x200
	ds_read_b64_tr_b16 v[74:75], v185 offset:0xa00
	s_waitcnt lgkmcnt(6)
	v_mfma_f32_32x32x16_bf16 v[0:15], v[88:91], v[76:79], v[0:15]
	ds_read_b64_tr_b16 v[76:77], v185 offset:0x1200
	ds_read_b64_tr_b16 v[78:79], v185 offset:0x1a00
	s_waitcnt lgkmcnt(6)
	v_mfma_f32_32x32x16_bf16 v[0:15], v[64:67], v[80:83], v[0:15]
	ds_read_b64_tr_b16 v[80:81], v185 offset:0x2200
	ds_read_b64_tr_b16 v[82:83], v185 offset:0x2a00
	s_waitcnt lgkmcnt(6)
	v_mfma_f32_32x32x16_bf16 v[0:15], v[68:71], v[84:87], v[0:15]
	ds_read_b64_tr_b16 v[84:85], v185 offset:0x3200
	ds_read_b64_tr_b16 v[86:87], v185 offset:0x3a00
	s_waitcnt lgkmcnt(15)
	s_waitcnt lgkmcnt(6)
	v_mfma_f32_32x32x16_bf16 v[48:63], v[96:99], v[72:75], v[48:63]
	ds_read_b64_tr_b16 v[72:73], v185 offset:0x400
	ds_read_b64_tr_b16 v[74:75], v185 offset:0xc00
	s_waitcnt lgkmcnt(6)
	v_mfma_f32_32x32x16_bf16 v[48:63], v[88:91], v[76:79], v[48:63]
	ds_read_b64_tr_b16 v[76:77], v185 offset:0x1400
	ds_read_b64_tr_b16 v[78:79], v185 offset:0x1c00
	s_waitcnt lgkmcnt(6)
	v_mfma_f32_32x32x16_bf16 v[48:63], v[64:67], v[80:83], v[48:63]
	ds_read_b64_tr_b16 v[80:81], v185 offset:0x2400
	ds_read_b64_tr_b16 v[82:83], v185 offset:0x2c00
	s_waitcnt lgkmcnt(6)
	v_mfma_f32_32x32x16_bf16 v[48:63], v[68:71], v[84:87], v[48:63]
	ds_read_b64_tr_b16 v[84:85], v185 offset:0x3400
	ds_read_b64_tr_b16 v[86:87], v185 offset:0x3c00
	s_waitcnt lgkmcnt(15)
	s_waitcnt lgkmcnt(6)
	v_mfma_f32_32x32x16_bf16 v[32:47], v[96:99], v[72:75], v[32:47]
	ds_read_b64_tr_b16 v[72:73], v185 offset:0x600
	ds_read_b64_tr_b16 v[74:75], v185 offset:0xe00
	s_waitcnt lgkmcnt(6)
	v_mfma_f32_32x32x16_bf16 v[32:47], v[88:91], v[76:79], v[32:47]
	ds_read_b64_tr_b16 v[76:77], v185 offset:0x1600
	ds_read_b64_tr_b16 v[78:79], v185 offset:0x1e00
	s_waitcnt lgkmcnt(6)
	v_mfma_f32_32x32x16_bf16 v[32:47], v[64:67], v[80:83], v[32:47]
	ds_read_b64_tr_b16 v[80:81], v185 offset:0x2600
	ds_read_b64_tr_b16 v[82:83], v185 offset:0x2e00
	s_waitcnt lgkmcnt(6)
	v_mfma_f32_32x32x16_bf16 v[32:47], v[68:71], v[84:87], v[32:47]
	ds_read_b64_tr_b16 v[84:85], v185 offset:0x3600
	ds_read_b64_tr_b16 v[86:87], v185 offset:0x3e00
	s_waitcnt lgkmcnt(15)
	s_waitcnt lgkmcnt(6)
	v_mfma_f32_32x32x16_bf16 v[16:31], v[96:99], v[72:75], v[16:31]
	v_mov_b32_e32 v186, v100
	s_waitcnt lgkmcnt(4)
	v_mfma_f32_32x32x16_bf16 v[16:31], v[88:91], v[76:79], v[16:31]
	s_waitcnt lgkmcnt(2)
	v_mfma_f32_32x32x16_bf16 v[16:31], v[64:67], v[80:83], v[16:31]
	s_waitcnt lgkmcnt(0)
	v_mfma_f32_32x32x16_bf16 v[16:31], v[68:71], v[84:87], v[16:31]
